# g2_vmcnt0_hoisted_out_of_scan_loop
# baseline (speedup 1.0000x reference)
.LBB0_1545:
	s_ashr_i32 s0, s42, 2
	s_and_b32 s0, s0, -8
	s_and_b32 s1, s42, 7
	s_or_b32 s0, s0, s1
	s_cmp_gt_i32 s0, 11
	s_cbranch_scc1 .LBB0_1544
	s_mul_hi_i32 s4, s0, 0x2aaaaaab
	s_lshr_b32 s1, s4, 31
	s_add_i32 s4, s4, s1
	s_mul_i32 s1, s4, 6
	s_lshr_b32 s12, s42, 3
	s_sub_i32 s5, s0, s1
	s_mov_b64 s[0:1], -1
	s_and_b64 vcc, exec, s[10:11]
	s_cbranch_vccz .LBB0_1550
	s_and_b32 s0, s12, 3
	s_waitcnt vmcnt(10)
	v_lshl_or_b32 v0, s0, 7, v126
	s_lshl_b32 s0, s5, 7
	s_ashr_i32 s1, s0, 31
	s_mul_i32 s9, s4, 0x6800000
	s_lshl_b64 s[0:1], s[0:1], 1
	s_mul_hi_i32 s8, s4, 0x6800000
	s_add_u32 s0, s0, s9
	s_addc_u32 s1, s1, s8
	v_lshrrev_b32_e32 v2, 3, v0
	v_mov_b64_e32 v[0:1], s[0:1]
	s_movk_i32 s0, 0x1a00
	v_mad_u64_u32 v[0:1], s[0:1], v2, s0, v[0:1]
	s_waitcnt vmcnt(1)
	v_lshl_add_u64 v[48:49], v[122:123], 0, v[0:1]
	v_mov_b32_e32 v0, 0
	s_mov_b32 s0, 0
	v_mov_b32_e32 v32, 0
	v_mov_b32_e32 v33, 0
	v_mov_b32_e32 v34, 0
	v_mov_b32_e32 v35, 0
	v_mov_b32_e32 v36, 0
	v_mov_b32_e32 v37, 0
	v_mov_b32_e32 v38, 0
	v_mov_b32_e32 v39, 0
	v_mov_b32_e32 v40, 0
	v_mov_b32_e32 v41, 0
	v_mov_b32_e32 v42, 0
	v_mov_b32_e32 v43, 0
	v_mov_b32_e32 v44, 0
	v_mov_b32_e32 v45, 0
	v_mov_b32_e32 v46, 0
	v_mov_b32_e32 v47, 0
	v_mov_b32_e32 v1, v0
	v_mov_b32_e32 v2, v0
	v_mov_b32_e32 v3, v0
	v_mov_b32_e32 v4, v0
	v_mov_b32_e32 v5, v0
	v_mov_b32_e32 v6, v0
	v_mov_b32_e32 v7, v0
	v_mov_b32_e32 v8, v0
	v_mov_b32_e32 v9, v0
	v_mov_b32_e32 v10, v0
	v_mov_b32_e32 v11, v0
	v_mov_b32_e32 v12, v0
	v_mov_b32_e32 v13, v0
	v_mov_b32_e32 v14, v0
	v_mov_b32_e32 v15, v0
	v_mov_b32_e32 v16, v0
	v_mov_b32_e32 v17, v0
	v_mov_b32_e32 v18, v0
	v_mov_b32_e32 v19, v0
	v_mov_b32_e32 v20, v0
	v_mov_b32_e32 v21, v0
	v_mov_b32_e32 v22, v0
	v_mov_b32_e32 v23, v0
	v_mov_b32_e32 v24, v0
	v_mov_b32_e32 v25, v0
	v_mov_b32_e32 v26, v0
	v_mov_b32_e32 v27, v0
	v_mov_b32_e32 v28, v0
	v_mov_b32_e32 v29, v0
	v_mov_b32_e32 v30, v0
	v_mov_b32_e32 v31, v0
	s_waitcnt vmcnt(0)
	s_barrier
.LBB0_1548:
	s_and_b32 s1, s0, 1
	s_lshl_b32 s8, s1, 16
	s_add_i32 s8, s8, 0
	s_lshl_b32 s1, s1, 2
	s_add_i32 s9, s8, s79
	s_add_i32 s1, s1, 0
	v_add_u32_e32 v50, s9, v124
	s_add_i32 s1, s1, 0x20000
	ds_read_b128 v[52:55], v50 offset:57344
	ds_read_b128 v[56:59], v50 offset:57360
	v_mov_b32_e32 v50, s1
	v_add_u32_e32 v51, s8, v120
	ds_read_b32 v50, v50
	ds_read_b128 v[60:63], v51
	ds_read_b128 v[64:67], v51 offset:4096
	ds_read_b128 v[68:71], v51 offset:1024
	ds_read_b128 v[72:75], v51 offset:20480
	ds_read_b128 v[76:79], v51 offset:17408
	ds_read_b128 v[80:83], v51 offset:8192
	ds_read_b128 v[84:87], v51 offset:5120
	ds_read_b128 v[88:91], v51 offset:24576
	ds_read_b128 v[92:95], v51 offset:21504
	ds_read_b128 v[96:99], v51 offset:12288
	ds_read_b128 v[100:103], v51 offset:9216
	ds_read_b128 v[104:107], v51 offset:28672
	ds_read_b128 v[108:111], v51 offset:25600
	ds_read_b128 v[112:115], v51 offset:16384
	ds_read_b128 v[116:119], v51 offset:13312
	ds_read_b128 v[128:131], v51 offset:29696
	s_waitcnt lgkmcnt(8)
	s_waitcnt lgkmcnt(14)
	v_mfma_f32_16x16x32_bf16 v[60:63], v[60:63], v[44:47], 0
	s_waitcnt lgkmcnt(2)
	v_mfma_f32_16x16x32_bf16 v[112:115], v[112:115], v[44:47], 0
	v_mfma_f32_16x16x32_bf16 v[64:67], v[64:67], v[44:47], 0
	v_mfma_f32_16x16x32_bf16 v[72:75], v[72:75], v[44:47], 0
	v_mfma_f32_16x16x32_bf16 v[80:83], v[80:83], v[44:47], 0
	v_mfma_f32_16x16x32_bf16 v[88:91], v[88:91], v[44:47], 0
	v_mfma_f32_16x16x32_bf16 v[96:99], v[96:99], v[44:47], 0
	v_mfma_f32_16x16x32_bf16 v[44:47], v[104:107], v[44:47], 0
	ds_read_b128 v[104:107], v51 offset:2048
	ds_read_b128 v[132:135], v51 offset:6144
	ds_read_b128 v[136:139], v51 offset:18432
	ds_read_b128 v[140:143], v51 offset:22528
	ds_read_b128 v[144:147], v51 offset:10240
	ds_read_b128 v[148:151], v51 offset:14336
	ds_read_b128 v[152:155], v51 offset:26624
	ds_read_b128 v[156:159], v51 offset:30720
	s_waitcnt lgkmcnt(8)
	v_mfma_f32_16x16x32_bf16 v[60:63], v[68:71], v[40:43], v[60:63]
	v_mfma_f32_16x16x32_bf16 v[68:71], v[76:79], v[40:43], v[112:115]
	v_mfma_f32_16x16x32_bf16 v[64:67], v[84:87], v[40:43], v[64:67]
	v_mfma_f32_16x16x32_bf16 v[72:75], v[92:95], v[40:43], v[72:75]
	v_mfma_f32_16x16x32_bf16 v[76:79], v[100:103], v[40:43], v[80:83]
	v_mfma_f32_16x16x32_bf16 v[80:83], v[108:111], v[40:43], v[88:91]
	s_waitcnt lgkmcnt(9)
	v_mfma_f32_16x16x32_bf16 v[84:87], v[116:119], v[40:43], v[96:99]
	s_waitcnt lgkmcnt(8)
	v_mfma_f32_16x16x32_bf16 v[40:43], v[128:131], v[40:43], v[44:47]
	s_nop 2
	ds_read_b128 v[44:47], v51 offset:3072
	ds_read_b128 v[88:91], v51 offset:7168
	ds_read_b128 v[92:95], v51 offset:19456
	ds_read_b128 v[96:99], v51 offset:23552
	ds_read_b128 v[100:103], v51 offset:11264
	ds_read_b128 v[108:111], v51 offset:15360
	ds_read_b128 v[112:115], v51 offset:27648
	ds_read_b128 v[116:119], v51 offset:31744
	s_waitcnt lgkmcnt(8)
	s_waitcnt lgkmcnt(14)
	v_mfma_f32_16x16x32_bf16 v[60:63], v[104:107], v[36:39], v[60:63]
	s_waitcnt lgkmcnt(13)
	v_mfma_f32_16x16x32_bf16 v[68:71], v[136:139], v[36:39], v[68:71]
	v_mfma_f32_16x16x32_bf16 v[64:67], v[132:135], v[36:39], v[64:67]
	s_waitcnt lgkmcnt(12)
	v_mfma_f32_16x16x32_bf16 v[72:75], v[140:143], v[36:39], v[72:75]
	s_waitcnt lgkmcnt(11)
	v_mfma_f32_16x16x32_bf16 v[76:79], v[144:147], v[36:39], v[76:79]
	s_waitcnt lgkmcnt(9)
	v_mfma_f32_16x16x32_bf16 v[80:83], v[152:155], v[36:39], v[80:83]
	v_mfma_f32_16x16x32_bf16 v[84:87], v[148:151], v[36:39], v[84:87]
	s_waitcnt lgkmcnt(8)
	v_mfma_f32_16x16x32_bf16 v[36:39], v[156:159], v[36:39], v[40:43]
	s_nop 2
	ds_read_b128 v[40:43], v51 offset:49152
	ds_read_b128 v[104:107], v51 offset:50176
	ds_read_b128 v[128:131], v51 offset:51200
	ds_read_b128 v[132:135], v51 offset:52224
	ds_read_b128 v[136:139], v51 offset:53248
	ds_read_b128 v[140:143], v51 offset:54272
	ds_read_b128 v[144:147], v51 offset:55296
	ds_read_b128 v[148:151], v51 offset:56320
	s_waitcnt lgkmcnt(8)
	s_waitcnt lgkmcnt(14)
	v_mfma_f32_16x16x32_bf16 v[44:47], v[44:47], v[32:35], v[60:63]
	s_waitcnt lgkmcnt(13)
	v_mfma_f32_16x16x32_bf16 v[60:63], v[92:95], v[32:35], v[68:71]
	v_mfma_f32_16x16x32_bf16 v[64:67], v[88:91], v[32:35], v[64:67]
	s_waitcnt lgkmcnt(12)
	v_mfma_f32_16x16x32_bf16 v[68:71], v[96:99], v[32:35], v[72:75]
	s_waitcnt lgkmcnt(11)
	v_mfma_f32_16x16x32_bf16 v[72:75], v[100:103], v[32:35], v[76:79]
	s_waitcnt lgkmcnt(9)
	v_mfma_f32_16x16x32_bf16 v[76:79], v[112:115], v[32:35], v[80:83]
	v_mfma_f32_16x16x32_bf16 v[80:83], v[108:111], v[32:35], v[84:87]
	s_waitcnt lgkmcnt(8)
	v_mfma_f32_16x16x32_bf16 v[32:35], v[116:119], v[32:35], v[36:39]
	s_nop 2
	v_lshlrev_b32_e32 v36, 16, v52
	v_and_b32_e32 v37, 0xffff0000, v52
	v_lshlrev_b32_e32 v38, 16, v53
	v_and_b32_e32 v39, 0xffff0000, v53
	v_sub_f32_e32 v36, v36, v44
	v_sub_f32_e32 v37, v37, v45
	v_sub_f32_e32 v38, v38, v46
	v_sub_f32_e32 v39, v39, v47
	v_lshlrev_b32_e32 v44, 16, v54
	v_and_b32_e32 v45, 0xffff0000, v54
	v_lshlrev_b32_e32 v46, 16, v55
	v_and_b32_e32 v47, 0xffff0000, v55
	v_lshlrev_b32_e32 v52, 16, v56
	v_and_b32_e32 v53, 0xffff0000, v56
	v_lshlrev_b32_e32 v54, 16, v57
	v_and_b32_e32 v55, 0xffff0000, v57
	v_lshlrev_b32_e32 v56, 16, v58
	v_and_b32_e32 v57, 0xffff0000, v58
	v_lshlrev_b32_e32 v58, 16, v59
	v_and_b32_e32 v59, 0xffff0000, v59
	v_sub_f32_e32 v44, v44, v64
	v_sub_f32_e32 v45, v45, v65
	v_sub_f32_e32 v46, v46, v66
	v_sub_f32_e32 v47, v47, v67
	v_sub_f32_e32 v52, v52, v72
	v_sub_f32_e32 v53, v53, v73
	v_sub_f32_e32 v54, v54, v74
	v_sub_f32_e32 v55, v55, v75
	v_sub_f32_e32 v56, v56, v80
	v_sub_f32_e32 v57, v57, v81
	v_sub_f32_e32 v58, v58, v82
	v_sub_f32_e32 v59, v59, v83
	v_cvt_pk_bf16_f32 v36, v36, v37
	v_cvt_pk_bf16_f32 v37, v38, v39
	v_cvt_pk_bf16_f32 v38, v44, v45
	v_cvt_pk_bf16_f32 v39, v46, v47
	v_cvt_pk_bf16_f32 v44, v52, v53
	v_cvt_pk_bf16_f32 v45, v54, v55
	v_cvt_pk_bf16_f32 v46, v56, v57
	v_cvt_pk_bf16_f32 v47, v58, v59
	ds_read_b128 v[52:55], v51 offset:32768
	ds_read_b128 v[56:59], v51 offset:33792
	ds_read_b128 v[64:67], v51 offset:34816
	ds_read_b128 v[72:75], v51 offset:35840
	ds_read_b128 v[80:83], v51 offset:36864
	ds_read_b128 v[84:87], v51 offset:37888
	ds_read_b128 v[88:91], v51 offset:38912
	ds_read_b128 v[92:95], v51 offset:39936
	s_waitcnt lgkmcnt(8)
	s_waitcnt lgkmcnt(14)
	v_mfma_f32_16x16x32_bf16 v[40:43], v[40:43], v[36:39], v[60:63]
	s_waitcnt lgkmcnt(9)
	v_mfma_f32_16x16x32_bf16 v[32:35], v[144:147], v[36:39], v[32:35]
	v_mfma_f32_16x16x32_bf16 v[40:43], v[104:107], v[44:47], v[40:43]
	v_mfma_f32_16x16x32_bf16 v[60:63], v[128:131], v[36:39], v[68:71]
	v_mfma_f32_16x16x32_bf16 v[68:71], v[136:139], v[36:39], v[76:79]
	s_waitcnt lgkmcnt(8)
	v_mfma_f32_16x16x32_bf16 v[32:35], v[148:151], v[44:47], v[32:35]
	v_mfma_f32_16x16x32_bf16 v[60:63], v[132:135], v[44:47], v[60:63]
	v_mfma_f32_16x16x32_bf16 v[68:71], v[140:143], v[44:47], v[68:71]
	ds_read_b128 v[76:79], v51 offset:40960
	ds_read_b128 v[96:99], v51 offset:41984
	ds_read_b128 v[100:103], v51 offset:43008
	ds_read_b128 v[104:107], v51 offset:44032
	ds_read_b128 v[108:111], v51 offset:45056
	ds_read_b128 v[112:115], v51 offset:46080
	ds_read_b128 v[116:119], v51 offset:47104
	ds_read_b128 v[128:131], v51 offset:48128
	s_waitcnt lgkmcnt(8)
	v_pk_mul_f32 v[2:3], v[2:3], v[50:51] op_sel_hi:[1,0]
	v_pk_mul_f32 v[0:1], v[0:1], v[50:51] op_sel_hi:[1,0]
	v_pk_mul_f32 v[6:7], v[6:7], v[50:51] op_sel_hi:[1,0]
	v_pk_mul_f32 v[4:5], v[4:5], v[50:51] op_sel_hi:[1,0]
	v_pk_mul_f32 v[10:11], v[10:11], v[50:51] op_sel_hi:[1,0]
	v_pk_mul_f32 v[8:9], v[8:9], v[50:51] op_sel_hi:[1,0]
	v_pk_mul_f32 v[14:15], v[14:15], v[50:51] op_sel_hi:[1,0]
	v_pk_mul_f32 v[12:13], v[12:13], v[50:51] op_sel_hi:[1,0]
	s_waitcnt lgkmcnt(14)
	v_mfma_f32_16x16x32_bf16 v[0:3], v[52:55], v[36:39], v[0:3]
	s_waitcnt lgkmcnt(13)
	v_mfma_f32_16x16x32_bf16 v[4:7], v[64:67], v[36:39], v[4:7]
	s_waitcnt lgkmcnt(11)
	v_mfma_f32_16x16x32_bf16 v[8:11], v[80:83], v[36:39], v[8:11]
	s_waitcnt lgkmcnt(9)
	v_mfma_f32_16x16x32_bf16 v[12:15], v[88:91], v[36:39], v[12:15]
	v_mfma_f32_16x16x32_bf16 v[0:3], v[56:59], v[44:47], v[0:3]
	v_mfma_f32_16x16x32_bf16 v[4:7], v[72:75], v[44:47], v[4:7]
	v_mfma_f32_16x16x32_bf16 v[8:11], v[84:87], v[44:47], v[8:11]
	s_waitcnt lgkmcnt(8)
	v_mfma_f32_16x16x32_bf16 v[12:15], v[92:95], v[44:47], v[12:15]
	s_waitcnt lgkmcnt(0)
	v_mul_f32_e64 v18, v18, v50
	v_mul_f32_e64 v19, v19, v50
	v_pk_mul_f32 v[16:17], v[16:17], v[50:51] op_sel_hi:[1,0]
	v_pk_mul_f32 v[22:23], v[22:23], v[50:51] op_sel_hi:[1,0]
	v_pk_mul_f32 v[20:21], v[20:21], v[50:51] op_sel_hi:[1,0]
	v_pk_mul_f32 v[26:27], v[26:27], v[50:51] op_sel_hi:[1,0]
	v_pk_mul_f32 v[24:25], v[24:25], v[50:51] op_sel_hi:[1,0]
	v_pk_mul_f32 v[30:31], v[30:31], v[50:51] op_sel_hi:[1,0]
	v_pk_mul_f32 v[28:29], v[28:29], v[50:51] op_sel_hi:[1,0]
	s_waitcnt lgkmcnt(7)
	v_mfma_f32_16x16x32_bf16 v[16:19], v[76:79], v[36:39], v[16:19]
	s_waitcnt lgkmcnt(5)
	v_mfma_f32_16x16x32_bf16 v[20:23], v[100:103], v[36:39], v[20:23]
	s_waitcnt lgkmcnt(3)
	v_mfma_f32_16x16x32_bf16 v[24:27], v[108:111], v[36:39], v[24:27]
	s_waitcnt lgkmcnt(1)
	v_mfma_f32_16x16x32_bf16 v[28:31], v[116:119], v[36:39], v[28:31]
	v_mfma_f32_16x16x32_bf16 v[16:19], v[96:99], v[44:47], v[16:19]
	v_mfma_f32_16x16x32_bf16 v[20:23], v[104:107], v[44:47], v[20:23]
	v_mfma_f32_16x16x32_bf16 v[24:27], v[112:115], v[44:47], v[24:27]
	s_waitcnt lgkmcnt(0)
	v_mfma_f32_16x16x32_bf16 v[28:31], v[128:131], v[44:47], v[28:31]
	v_cvt_pk_bf16_f32 v36, v40, v41
	v_cvt_pk_bf16_f32 v37, v42, v43
	v_cvt_pk_bf16_f32 v38, v60, v61
	v_cvt_pk_bf16_f32 v39, v62, v63
	v_cvt_pk_bf16_f32 v40, v68, v69
	v_cvt_pk_bf16_f32 v41, v70, v71
	v_cvt_pk_bf16_f32 v42, v32, v33
	v_cvt_pk_bf16_f32 v43, v34, v35
	s_add_i32 s0, s0, 1
	s_mov_b64 s[8:9], 0x68000
	global_store_dwordx4 v[48:49], v[36:39], off
	global_store_dwordx4 v[48:49], v[40:43], off offset:16
	v_cvt_pk_bf16_f32 v44, v0, v1
	v_cvt_pk_bf16_f32 v45, v2, v3
	v_cvt_pk_bf16_f32 v46, v4, v5
	v_cvt_pk_bf16_f32 v47, v6, v7
	v_cvt_pk_bf16_f32 v40, v8, v9
	v_cvt_pk_bf16_f32 v41, v10, v11
	v_cvt_pk_bf16_f32 v42, v12, v13
	v_cvt_pk_bf16_f32 v43, v14, v15
	v_cvt_pk_bf16_f32 v36, v16, v17
	v_cvt_pk_bf16_f32 v37, v18, v19
	v_cvt_pk_bf16_f32 v38, v20, v21
	v_cvt_pk_bf16_f32 v39, v22, v23
	v_cvt_pk_bf16_f32 v32, v24, v25
	v_cvt_pk_bf16_f32 v33, v26, v27
	v_cvt_pk_bf16_f32 v34, v28, v29
	v_cvt_pk_bf16_f32 v35, v30, v31
	v_lshl_add_u64 v[48:49], v[48:49], 0, s[8:9]
	s_cmpk_lg_i32 s0, 0x100
	s_barrier
	s_cbranch_scc1 .LBB0_1548
	s_mov_b64 s[0:1], 0
